# v130 + phase-3b GDN head-output items visited newest-snapshot-first (k=1,3,5,7,0,2,4,6)
# speedup vs baseline: 1.0244x; 1.0017x over previous
.LBB0_1029:
	s_cmpk_gt_i32 s2, 0xfff
	s_cbranch_scc1 .LBB0_1032
	s_add_u32 s15, s20, 0x17348000
	s_addc_u32 s16, s21, 0
	s_add_u32 s100, s20, 0x10000
	s_addc_u32 s101, s21, 0
	s_waitcnt vmcnt(30)
	v_mbcnt_hi_u32_b32 v20, -1, v183
	s_add_u32 s17, s20, 0x15248000
	v_and_b32_e32 v0, 64, v20
	s_mov_b32 s0, 0x358637bd
	s_addc_u32 s29, s21, 0
	s_mov_b32 s9, 0
	v_mov_b32_e32 v9, 0
	s_mov_b64 s[10:11], 0x1000
	s_mov_b64 s[12:13], 0x1800
	s_movk_i32 s34, 0x1000
	v_xor_b32_e32 v21, 1, v20
	v_add_u32_e32 v22, 64, v0
	v_xor_b32_e32 v23, 2, v20
	s_waitcnt vmcnt(29)
	v_xor_b32_e32 v24, 4, v20
	v_xor_b32_e32 v25, 8, v20
	s_mov_b32 s14, 0x3c800000
	v_mov_b64_e32 v[10:11], s[0:1]
	s_mov_b32 s35, 0x800000
	s_movk_i32 s36, 0x2000
	s_movk_i32 s37, 0x4000
	s_movk_i32 s38, 0x6000
	s_add_i32 s39, s2, 0x200
.LBB0_1031:
	v_cmp_lt_i32_e32 vcc, v21, v22
	v_mov_b32_e32 v0, v181
	s_ashr_i32 s0, s39, 3
	v_cndmask_b32_e32 v2, v20, v21, vcc
	v_cmp_lt_i32_e32 vcc, v23, v22
	s_waitcnt vmcnt(28)
	v_lshlrev_b32_e32 v33, 2, v2
	v_ashrrev_i32_e32 v2, 6, v0
	v_cndmask_b32_e32 v3, v20, v23, vcc
	v_cmp_lt_i32_e32 vcc, v24, v22
	v_lshlrev_b32_e32 v32, 2, v3
	v_and_b32_e32 v3, 63, v0
	v_cndmask_b32_e32 v4, v20, v24, vcc
	v_cmp_lt_i32_e32 vcc, v25, v22
	v_lshlrev_b32_e32 v31, 2, v4
	v_and_b32_e32 v4, 15, v0
	v_cndmask_b32_e32 v5, v20, v25, vcc
	v_lshlrev_b32_e32 v30, 2, v5
	v_lshrrev_b32_e32 v0, 2, v0
	v_lshlrev_b32_e32 v5, 4, v2
	s_lshl_b32 s1, s39, 7
	v_and_b32_e32 v6, 12, v0
	v_lshlrev_b32_e32 v7, 2, v3
	v_lshlrev_b32_e32 v12, 5, v3
	v_lshl_add_u32 v3, s0, 6, v5
	s_and_b32 s4, s39, 0xfffffc00
	s_and_b32 s8, s1, 0x380
	v_lshlrev_b32_e32 v8, 1, v4
	v_lshlrev_b32_e32 v0, 2, v4
	v_or_b32_e32 v5, v5, v4
	v_or_b32_e32 v4, v3, v6
	s_and_b32 s1, s0, 0x7f
	s_or_b32 s4, s8, s4
	global_load_dword v29, v0, s[40:41]
	global_load_dword v28, v0, s[40:41] offset:64
	global_load_dword v27, v0, s[40:41] offset:128
	global_load_dword v26, v0, s[40:41] offset:192
	v_lshlrev_b32_e32 v0, 1, v6
	v_lshlrev_b32_e32 v6, 6, v5
	v_ashrrev_i32_e32 v5, 31, v4
	s_or_b32 s4, s4, s1
	s_waitcnt vmcnt(28)
	v_lshlrev_b64 v[66:67], 13, v[4:5]
	s_ashr_i32 s5, s4, 31
	v_or_b32_e32 v14, 1, v4
	v_or_b32_e32 v16, 2, v4
	v_or_b32_e32 v18, 3, v4
	v_lshl_add_u64 v[4:5], s[20:21], 0, v[66:67]
	s_lshl_b64 s[0:1], s[4:5], 13
	v_lshl_add_u64 v[4:5], v[4:5], 0, s[8:9]
	s_add_u32 s4, s50, s0
	v_lshl_add_u64 v[50:51], v[4:5], 0, v[8:9]
	s_addc_u32 s5, s51, s1
	v_add_co_u32_e32 v52, vcc, s36, v50
	s_add_u32 s6, s17, s0
	s_nop 0
	v_addc_co_u32_e32 v53, vcc, 0, v51, vcc
	v_lshl_or_b32 v2, v2, 10, v7
	v_ashrrev_i32_e32 v7, 31, v6
	s_addc_u32 s7, s29, s1
	v_add_co_u32_e32 v54, vcc, s37, v50
	v_mov_b32_e32 v1, v9
	v_ashrrev_i32_e32 v3, 31, v2
	v_lshl_add_u64 v[6:7], v[6:7], 1, s[4:5]
	s_add_u32 s0, s15, s0
	v_addc_co_u32_e32 v55, vcc, 0, v51, vcc
	v_mov_b32_e32 v13, v9
	v_lshl_add_u64 v[34:35], v[6:7], 0, v[0:1]
	v_lshl_add_u64 v[36:37], v[2:3], 1, s[6:7]
	s_addc_u32 s1, s16, s1
	v_add_co_u32_e32 v56, vcc, s38, v50
	global_load_dwordx2 v[4:5], v[34:35], off
	global_load_dwordx2 v[6:7], v[34:35], off offset:32
	global_load_dwordx2 v[0:1], v[34:35], off offset:64
	global_load_dwordx2 v[2:3], v[34:35], off offset:96
	global_load_dwordx2 v[68:69], v[36:37], off
	global_load_dwordx2 v[72:73], v[36:37], off offset:512
	global_load_dwordx2 v[76:77], v[36:37], off offset:1024
	global_load_dwordx2 v[80:81], v[36:37], off offset:1536
	v_addc_co_u32_e32 v57, vcc, 0, v51, vcc
	global_load_ushort v82, v[50:51], off offset:3072
	global_load_ushort v83, v[50:51], off offset:3104
	global_load_ushort v84, v[50:51], off offset:3136
	global_load_ushort v85, v[50:51], off offset:3168
	global_load_dwordx4 v[34:37], v12, s[0:1]
	global_load_dwordx4 v[38:41], v12, s[0:1] offset:2048
	global_load_dwordx4 v[42:45], v12, s[0:1] offset:16
	global_load_dwordx4 v[46:49], v12, s[0:1] offset:2064
	global_load_ushort v86, v[52:53], off offset:3072
	global_load_ushort v87, v[54:55], off offset:3072
	global_load_ushort v88, v[56:57], off offset:3072
	global_load_ushort v89, v[52:53], off offset:3104
	global_load_ushort v90, v[54:55], off offset:3104
	global_load_ushort v91, v[56:57], off offset:3104
	global_load_ushort v92, v[52:53], off offset:3136
	global_load_ushort v93, v[54:55], off offset:3136
	global_load_ushort v94, v[56:57], off offset:3136
	global_load_ushort v95, v[54:55], off offset:3168
	global_load_ushort v96, v[52:53], off offset:3168
	global_load_ushort v97, v[56:57], off offset:3168
	v_lshl_add_u64 v[12:13], s[0:1], 0, v[12:13]
	v_lshl_add_u64 v[70:71], v[12:13], 0, s[10:11]
	s_waitcnt vmcnt(55)
	v_lshl_add_u64 v[74:75], v[12:13], 0, s[12:13]
	v_add_co_u32_e32 v12, vcc, s34, v12
	s_add_u32 s0, s20, s8
	s_nop 0
	v_addc_co_u32_e32 v13, vcc, 0, v13, vcc
	global_load_dwordx4 v[50:53], v[12:13], off
	global_load_dwordx4 v[54:57], v[12:13], off offset:2048
	global_load_dwordx4 v[58:61], v[70:71], off offset:16
	global_load_dwordx4 v[62:65], v[74:75], off offset:16
	s_addc_u32 s1, s21, 0
	v_and_b32_e32 v12, 0xffe00000, v66
	v_lshrrev_b32_e32 v13, 5, v66
	v_and_b32_e32 v13, 0xe000, v13
	v_lshrrev_b32_e32 v14, 7, v66
	v_and_b32_e32 v14, 0x7c0, v14
	v_lshrrev_b32_e32 v15, 10, v66
	v_and_b32_e32 v15, 32, v15
	v_and_b32_e32 v16, 30, v8
	v_or3_b32 v12, v12, v13, v14
	v_or3_b32 v12, v12, v15, v16
	s_lshl_b32 s8, s8, 10
	v_add_u32_e32 v12, s8, v12
	v_xor_b32_e32 v16, 16, v12
	v_add_u32_e32 v14, 64, v12
	v_add_u32_e32 v18, 0xc0, v16
	v_add_u32_e32 v16, 0x80, v16
	v_xor_b32_e32 v13, 32, v12
	v_xor_b32_e32 v15, 32, v14
	v_xor_b32_e32 v17, 32, v16
	v_xor_b32_e32 v19, 32, v18
	s_add_i32 s8, s39, 0x400
	s_cmpk_lt_i32 s8, 0x1000
	s_cbranch_scc1 .Lp3b_nx
	s_and_b32 s8, s39, 0x1ff
	s_bitcmp1_b32 s39, 9
.Lp3b_nx:
	s_mov_b32 s39, s8
	s_waitcnt vmcnt(23)
	v_lshlrev_b32_e32 v8, 16, v82
	s_waitcnt vmcnt(22)
	v_lshlrev_b32_e32 v98, 16, v83
	s_waitcnt vmcnt(21)
	v_lshlrev_b32_e32 v99, 16, v84
	s_waitcnt vmcnt(20)
	v_lshlrev_b32_e32 v100, 16, v85
	s_waitcnt vmcnt(19)
	v_mov_b32_e32 v82, v34
	v_mov_b32_e32 v83, v35
	s_waitcnt vmcnt(18)
	v_mov_b32_e32 v84, v38
	v_mov_b32_e32 v85, v39
	s_waitcnt vmcnt(17)
	v_mov_b32_e32 v34, v42
	v_mov_b32_e32 v35, v43
	v_mul_f32_e32 v42, 0xbfb8aa3b, v8
	v_mul_f32_e32 v43, 0xbfb8aa3b, v98
	v_mov_b32_e32 v38, v36
	v_mov_b32_e32 v39, v37
	v_lshlrev_b32_e32 v66, 16, v68
	v_and_b32_e32 v67, 0xffff0000, v68
	v_lshlrev_b32_e32 v68, 16, v69
	v_and_b32_e32 v69, 0xffff0000, v69
	v_lshlrev_b32_e32 v70, 16, v72
	v_and_b32_e32 v71, 0xffff0000, v72
	v_lshlrev_b32_e32 v72, 16, v73
	v_and_b32_e32 v73, 0xffff0000, v73
	s_waitcnt vmcnt(16)
	v_mov_b32_e32 v36, v46
	v_mov_b32_e32 v37, v47
	v_mov_b32_e32 v46, v44
	v_mov_b32_e32 v47, v45
	v_exp_f32_e32 v103, v42
	v_exp_f32_e32 v107, v43
	v_mfma_f32_16x16x32_bf16 v[42:45], v[4:7], v[82:85], v[66:69]
	v_lshlrev_b32_e32 v74, 16, v76
	v_and_b32_e32 v75, 0xffff0000, v76
	v_lshlrev_b32_e32 v76, 16, v77
	v_and_b32_e32 v77, 0xffff0000, v77
	v_lshlrev_b32_e32 v78, 16, v80
	v_and_b32_e32 v79, 0xffff0000, v80
	v_lshlrev_b32_e32 v80, 16, v81
	v_and_b32_e32 v81, 0xffff0000, v81
	s_waitcnt vmcnt(15)
	v_lshlrev_b32_e32 v86, 16, v86
	s_waitcnt vmcnt(14)
	v_lshlrev_b32_e32 v87, 16, v87
	v_mul_f32_e32 v101, 0xbfb8aa3b, v99
	v_mfma_f32_16x16x32_bf16 v[38:41], v[4:7], v[38:41], v[70:73]
	s_waitcnt vmcnt(8)
	v_lshlrev_b32_e32 v93, 16, v93
	s_waitcnt vmcnt(7)
	v_lshlrev_b32_e32 v94, 16, v94
	v_mul_f32_e32 v104, 0xbfb8aa3b, v86
	v_mul_f32_e32 v105, 0xbfb8aa3b, v87
	v_exp_f32_e32 v67, v101
	v_mfma_f32_16x16x32_bf16 v[34:37], v[4:7], v[34:37], v[74:77]
	v_lshlrev_b32_e32 v88, 16, v88
	v_lshlrev_b32_e32 v89, 16, v89
	v_lshlrev_b32_e32 v90, 16, v90
	v_mfma_f32_16x16x32_bf16 v[4:7], v[4:7], v[46:49], v[78:81]
	v_lshlrev_b32_e32 v92, 16, v92
	s_waitcnt vmcnt(5)
	v_lshlrev_b32_e32 v96, 16, v96
	v_lshlrev_b32_e32 v95, 16, v95
	v_mul_f32_e32 v69, 0xbfb8aa3b, v93
	v_mul_f32_e32 v70, 0xbfb8aa3b, v94
	s_waitcnt vmcnt(3)
	v_mov_b32_e32 v46, v50
	v_mov_b32_e32 v47, v51
	s_waitcnt vmcnt(2)
	v_mov_b32_e32 v48, v54
	v_mov_b32_e32 v49, v55
	s_waitcnt vmcnt(1)
	v_mov_b32_e32 v50, v58
	v_mov_b32_e32 v51, v59
	v_exp_f32_e32 v58, v104
	v_exp_f32_e32 v59, v105
	v_lshlrev_b32_e32 v91, 16, v91
	v_mul_f32_e32 v102, 0xbfb8aa3b, v100
	v_lshlrev_b32_e32 v97, 16, v97
	v_mul_f32_e32 v106, 0xbfb8aa3b, v88
	v_mul_f32_e32 v108, 0xbfb8aa3b, v89
	v_mul_f32_e32 v109, 0xbfb8aa3b, v90
	v_mul_f32_e32 v68, 0xbfb8aa3b, v92
	v_mul_f32_e32 v72, 0xbfb8aa3b, v96
	v_mul_f32_e32 v73, 0xbfb8aa3b, v95
	v_mov_b32_e32 v54, v52
	v_mov_b32_e32 v55, v53
	v_mfma_f32_16x16x32_bf16 v[42:45], v[0:3], v[46:49], v[42:45]
	v_exp_f32_e32 v46, v69
	v_exp_f32_e32 v47, v70
	v_mul_f32_e32 v66, 0xbfb8aa3b, v91
	v_exp_f32_e32 v71, v102
	v_mul_f32_e32 v74, 0xbfb8aa3b, v97
	s_waitcnt vmcnt(0)
	v_mov_b32_e32 v52, v62
	v_mov_b32_e32 v53, v63
	v_mov_b32_e32 v62, v60
	v_mov_b32_e32 v63, v61
	v_exp_f32_e32 v60, v106
	v_exp_f32_e32 v61, v108
	v_exp_f32_e32 v75, v109
	v_exp_f32_e32 v68, v68
	v_exp_f32_e32 v48, v72
	v_mfma_f32_16x16x32_bf16 v[38:41], v[0:3], v[54:57], v[38:41]
	v_exp_f32_e32 v49, v73
	v_exp_f32_e32 v66, v66
	v_exp_f32_e32 v54, v74
	v_add_f32_e32 v55, 1.0, v103
	v_mfma_f32_16x16x32_bf16 v[34:37], v[0:3], v[50:53], v[34:37]
	v_add_f32_e32 v50, 1.0, v107
	v_add_f32_e32 v51, 1.0, v67
	v_add_f32_e32 v46, 1.0, v46
	v_mfma_f32_16x16x32_bf16 v[0:3], v[0:3], v[62:65], v[4:7]
	v_rcp_f32_e32 v62, v55
	v_add_f32_e32 v47, 1.0, v47
	v_add_f32_e32 v52, 1.0, v71
	v_add_f32_e32 v4, 1.0, v58
	v_add_f32_e32 v5, 1.0, v59
	v_rcp_f32_e32 v58, v50
	v_rcp_f32_e32 v59, v51
	v_add_f32_e32 v6, 1.0, v60
	v_add_f32_e32 v7, 1.0, v61
	v_add_f32_e32 v50, 1.0, v75
	v_add_f32_e32 v51, 1.0, v68
	v_add_f32_e32 v48, 1.0, v48
	v_add_f32_e32 v49, 1.0, v49
	v_rcp_f32_e32 v61, v4
	v_rcp_f32_e32 v63, v5
	v_rcp_f32_e32 v69, v46
	v_rcp_f32_e32 v70, v47
	v_mov_b32_e32 v4, v42
	v_mov_b32_e32 v5, v38
	v_mov_b32_e32 v46, v43
	v_mov_b32_e32 v47, v39
	v_add_f32_e32 v53, 1.0, v66
	v_rcp_f32_e32 v60, v52
	v_add_f32_e32 v52, 1.0, v54
	v_rcp_f32_e32 v64, v6
	v_rcp_f32_e32 v65, v7
	v_rcp_f32_e32 v66, v50
	v_rcp_f32_e32 v68, v51
	v_rcp_f32_e32 v71, v48
	v_rcp_f32_e32 v72, v49
	v_mov_b32_e32 v6, v34
	v_mov_b32_e32 v7, v0
	v_mov_b32_e32 v48, v35
	v_mov_b32_e32 v49, v1
	v_mov_b32_e32 v50, v44
	v_mov_b32_e32 v51, v40
	v_mov_b32_e32 v54, v45
	v_mov_b32_e32 v55, v41
	v_pk_mul_f32 v[4:5], v[4:5], v[4:5]
	v_pk_mul_f32 v[46:47], v[46:47], v[46:47]
	v_rcp_f32_e32 v67, v53
	v_rcp_f32_e32 v73, v52
	v_mov_b32_e32 v52, v36
	v_mov_b32_e32 v53, v2
	v_mov_b32_e32 v56, v37
	v_mov_b32_e32 v57, v3
	v_mul_f32_e32 v8, v62, v8
	v_mul_f32_e32 v62, v58, v98
	v_mul_f32_e32 v74, v59, v99
	v_pk_mul_f32 v[6:7], v[6:7], v[6:7]
	v_pk_mul_f32 v[48:49], v[48:49], v[48:49]
	v_pk_mul_f32 v[50:51], v[50:51], v[50:51]
	v_pk_mul_f32 v[54:55], v[54:55], v[54:55]
	v_mov_b32_e32 v58, v46
	v_mov_b32_e32 v59, v4
	v_mov_b32_e32 v4, v47
	v_pk_mul_f32 v[52:53], v[52:53], v[52:53]
	v_pk_mul_f32 v[56:57], v[56:57], v[56:57]
	v_mov_b32_e32 v46, v48
	v_mov_b32_e32 v47, v6
	v_mov_b32_e32 v6, v49
	v_mov_b32_e32 v48, v54
	v_mov_b32_e32 v49, v50
	v_mov_b32_e32 v50, v55
	v_pk_add_f32 v[4:5], v[58:59], v[4:5]
	v_mov_b32_e32 v54, v56
	v_mov_b32_e32 v55, v52
	v_pk_add_f32 v[48:49], v[48:49], v[50:51]
	v_pk_add_f32 v[4:5], v[4:5], v[46:47]
	v_mov_b32_e32 v52, v57
	v_pk_add_f32 v[46:47], v[48:49], v[54:55]
	v_pk_add_f32 v[4:5], v[4:5], v[6:7]
	v_pk_add_f32 v[6:7], v[46:47], v[52:53]
	ds_bpermute_b32 v47, v33, v5
	ds_bpermute_b32 v46, v33, v4
	ds_bpermute_b32 v49, v33, v7
	ds_bpermute_b32 v48, v33, v6
	v_mul_f32_e32 v60, v60, v100
	v_mul_f32_e32 v61, v61, v86
	s_waitcnt lgkmcnt(2)
	v_pk_add_f32 v[4:5], v[4:5], v[46:47]
	ds_bpermute_b32 v47, v32, v5
	s_waitcnt lgkmcnt(1)
	v_pk_add_f32 v[6:7], v[6:7], v[48:49]
	ds_bpermute_b32 v46, v32, v4
	ds_bpermute_b32 v33, v32, v7
	ds_bpermute_b32 v32, v32, v6
	v_mul_f32_e32 v63, v63, v87
	v_mul_f32_e32 v64, v64, v88
	s_waitcnt lgkmcnt(2)
	v_pk_add_f32 v[4:5], v[4:5], v[46:47]
	v_mul_f32_e32 v65, v65, v89
	s_waitcnt lgkmcnt(0)
	v_pk_add_f32 v[6:7], v[6:7], v[32:33]
	ds_bpermute_b32 v33, v31, v5
	ds_bpermute_b32 v32, v31, v4
	ds_bpermute_b32 v47, v31, v7
	ds_bpermute_b32 v46, v31, v6
	v_mul_f32_e32 v66, v66, v90
	v_mul_f32_e32 v67, v67, v91
	s_waitcnt lgkmcnt(2)
	v_pk_add_f32 v[4:5], v[4:5], v[32:33]
	ds_bpermute_b32 v33, v30, v5
	s_waitcnt lgkmcnt(1)
	v_pk_add_f32 v[6:7], v[6:7], v[46:47]
	ds_bpermute_b32 v32, v30, v4
	ds_bpermute_b32 v31, v30, v7
	ds_bpermute_b32 v30, v30, v6
	v_mul_f32_e32 v68, v68, v92
	v_mul_f32_e32 v69, v69, v93
	s_waitcnt lgkmcnt(2)
	v_pk_add_f32 v[4:5], v[4:5], v[32:33]
	v_mul_f32_e32 v70, v70, v94
	s_waitcnt lgkmcnt(0)
	v_pk_add_f32 v[6:7], v[6:7], v[30:31]
	v_pk_fma_f32 v[4:5], v[4:5], s[14:15], v[10:11] op_sel_hi:[1,0,0]
	v_pk_fma_f32 v[6:7], v[6:7], s[14:15], v[10:11] op_sel_hi:[1,0,0]
	v_mul_f32_e32 v30, 0x4b800000, v5
	v_cmp_gt_f32_e64 s[6:7], s35, v5
	v_mul_f32_e32 v31, 0x4b800000, v4
	v_cmp_gt_f32_e32 vcc, s35, v4
	v_mul_f32_e32 v32, 0x4b800000, v7
	v_mul_f32_e32 v33, 0x4b800000, v6
	v_cmp_gt_f32_e64 s[0:1], s35, v6
	v_cmp_gt_f32_e64 s[4:5], s35, v7
	v_cndmask_b32_e64 v5, v5, v30, s[6:7]
	v_cndmask_b32_e32 v4, v4, v31, vcc
	v_cndmask_b32_e64 v7, v7, v32, s[4:5]
	v_cndmask_b32_e64 v6, v6, v33, s[0:1]
	v_rsq_f32_e32 v5, v5
	v_rsq_f32_e32 v4, v4
	v_rsq_f32_e32 v7, v7
	v_rsq_f32_e32 v6, v6
	v_mul_f32_e32 v30, 0x45800000, v5
	v_mul_f32_e32 v31, 0x45800000, v4
	v_mul_f32_e32 v32, 0x45800000, v7
	v_mul_f32_e32 v33, 0x45800000, v6
	v_cndmask_b32_e64 v5, v5, v30, s[6:7]
	v_cndmask_b32_e32 v4, v4, v31, vcc
	v_cndmask_b32_e64 v7, v7, v32, s[4:5]
	v_cndmask_b32_e64 v6, v6, v33, s[0:1]
	v_mul_f32_e32 v30, v42, v5
	v_mul_f32_e32 v31, v43, v4
	v_mul_f32_e32 v32, v44, v7
	v_mul_f32_e32 v33, v45, v6
	v_mul_f32_e32 v38, v38, v5
	v_mul_f32_e32 v39, v39, v4
	v_mul_f32_e32 v40, v40, v7
	v_mul_f32_e32 v41, v41, v6
	v_mul_f32_e32 v34, v34, v5
	v_mul_f32_e32 v35, v35, v4
	v_mul_f32_e32 v36, v36, v7
	v_mul_f32_e32 v37, v37, v6
	v_mul_f32_e32 v0, v0, v5
	v_mul_f32_e32 v1, v1, v4
	v_mul_f32_e32 v2, v2, v7
	v_mul_f32_e32 v3, v3, v6
	v_mul_f32_e32 v4, v29, v30
	v_mul_f32_e32 v71, v71, v96
	v_mul_f32_e32 v72, v72, v95
	v_mul_f32_e32 v73, v73, v97
	v_mul_f32_e32 v5, v29, v31
	v_mul_f32_e32 v6, v29, v32
	v_mul_f32_e32 v7, v29, v33
	v_mul_f32_e32 v29, v28, v38
	v_mul_f32_e32 v30, v28, v39
	v_mul_f32_e32 v31, v28, v40
	v_mul_f32_e32 v28, v28, v41
	v_mul_f32_e32 v32, v27, v34
	v_mul_f32_e32 v33, v27, v35
	v_mul_f32_e32 v34, v27, v36
	v_mul_f32_e32 v27, v27, v37
	v_mul_f32_e32 v0, v26, v0
	v_mul_f32_e32 v1, v26, v1
	v_mul_f32_e32 v2, v26, v2
	v_mul_f32_e32 v3, v26, v3
	v_mul_f32_e32 v4, v8, v4
	v_mul_f32_e32 v5, v61, v5
	v_mul_f32_e32 v6, v63, v6
	v_mul_f32_e32 v7, v64, v7
	v_mul_f32_e32 v8, v62, v29
	v_mul_f32_e32 v26, v65, v30
	v_mul_f32_e32 v29, v66, v31
	v_mul_f32_e32 v28, v67, v28
	v_mul_f32_e32 v30, v74, v32
	v_mul_f32_e32 v31, v68, v33
	v_mul_f32_e32 v32, v69, v34
	v_mul_f32_e32 v27, v70, v27
	v_mul_f32_e32 v0, v60, v0
	v_mul_f32_e32 v1, v71, v1
	v_mul_f32_e32 v2, v72, v2
	v_mul_f32_e32 v3, v73, v3
	v_cvt_pk_bf16_f32 v4, v4, s0
	v_cvt_pk_bf16_f32 v5, v5, s0
	v_cvt_pk_bf16_f32 v6, v6, s0
	v_cvt_pk_bf16_f32 v7, v7, s0
	v_cvt_pk_bf16_f32 v8, v8, s0
	v_cvt_pk_bf16_f32 v26, v26, s0
	v_cvt_pk_bf16_f32 v29, v29, s0
	v_cvt_pk_bf16_f32 v28, v28, s0
	v_cvt_pk_bf16_f32 v30, v30, s0
	v_cvt_pk_bf16_f32 v31, v31, s0
	v_cvt_pk_bf16_f32 v32, v32, s0
	v_cvt_pk_bf16_f32 v27, v27, s0
	v_cvt_pk_bf16_f32 v0, v0, s0
	v_cvt_pk_bf16_f32 v1, v1, s0
	v_cvt_pk_bf16_f32 v2, v2, s0
	v_cvt_pk_bf16_f32 v3, v3, s0
	global_store_short v12, v4, s[20:21]
	global_store_short v14, v5, s[20:21]
	global_store_short v16, v6, s[20:21]
	global_store_short v18, v7, s[20:21]
	global_store_short v13, v8, s[20:21]
	global_store_short v15, v26, s[20:21]
	global_store_short v17, v29, s[20:21]
	global_store_short v19, v28, s[20:21]
	global_store_short v12, v30, s[100:101]
	global_store_short v14, v31, s[100:101]
	global_store_short v16, v32, s[100:101]
	global_store_short v18, v27, s[100:101]
	global_store_short v13, v0, s[100:101]
	global_store_short v15, v1, s[100:101]
	global_store_short v17, v2, s[100:101]
	global_store_short v19, v3, s[100:101]
	s_cbranch_scc1 .LBB0_1031
